# hyena conv: filter-norm partial loads hoisted above the MFMA loop, staging loads batched, Toeplitz MFMA loop software-pipelined; scan DMA m0 save/restore removed
# speedup vs baseline: 1.0122x; 1.0072x over previous
.LBB0_522:
	s_cmp_eq_u32 s28, 0
	s_cbranch_scc1 .Lcv_done
	s_waitcnt vmcnt(16)
	v_cvt_pk_bf16_f32 v196, v160, v161
	v_cvt_pk_bf16_f32 v197, v162, v163
	v_cvt_pk_bf16_f32 v198, v164, v165
	v_cvt_pk_bf16_f32 v199, v166, v167
	v_cvt_pk_bf16_f32 v200, v168, v169
	v_cvt_pk_bf16_f32 v201, v170, v171
	v_cvt_pk_bf16_f32 v202, v172, v173
	v_cvt_pk_bf16_f32 v203, v174, v175
	v_cvt_pk_bf16_f32 v204, v176, v177
	v_cvt_pk_bf16_f32 v205, v178, v179
	v_cvt_pk_bf16_f32 v206, v180, v181
	v_cvt_pk_bf16_f32 v207, v182, v183
	v_cvt_pk_bf16_f32 v208, v184, v185
	v_cvt_pk_bf16_f32 v209, v186, v187
	v_cvt_pk_bf16_f32 v210, v188, v189
	v_cvt_pk_bf16_f32 v211, v190, v191
	v_and_b32_e32 v192, 2, v234
	v_and_b32_e32 v193, 1, v234
	v_cmp_ne_u32_e64 s[18:19], 0, v192
	v_cmp_ne_u32_e64 s[98:99], 0, v193
	s_nop 3
	s_mov_b64 vcc, s[18:19]
	s_nop 1
	v_cndmask_b32_dpp v168, v196, v204, vcc quad_perm:[2,3,0,1] row_mask:0xf bank_mask:0xf
	v_cndmask_b32_dpp v169, v197, v205, vcc quad_perm:[2,3,0,1] row_mask:0xf bank_mask:0xf
	v_cndmask_b32_dpp v170, v198, v206, vcc quad_perm:[2,3,0,1] row_mask:0xf bank_mask:0xf
	v_cndmask_b32_dpp v171, v199, v207, vcc quad_perm:[2,3,0,1] row_mask:0xf bank_mask:0xf
	v_cndmask_b32_dpp v172, v200, v208, vcc quad_perm:[2,3,0,1] row_mask:0xf bank_mask:0xf
	v_cndmask_b32_dpp v173, v201, v209, vcc quad_perm:[2,3,0,1] row_mask:0xf bank_mask:0xf
	v_cndmask_b32_dpp v174, v202, v210, vcc quad_perm:[2,3,0,1] row_mask:0xf bank_mask:0xf
	v_cndmask_b32_dpp v175, v203, v211, vcc quad_perm:[2,3,0,1] row_mask:0xf bank_mask:0xf
	s_not_b64 vcc, s[18:19]
	s_nop 1
	v_cndmask_b32_dpp v160, v204, v196, vcc quad_perm:[2,3,0,1] row_mask:0xf bank_mask:0xf
	v_cndmask_b32_dpp v161, v205, v197, vcc quad_perm:[2,3,0,1] row_mask:0xf bank_mask:0xf
	v_cndmask_b32_dpp v162, v206, v198, vcc quad_perm:[2,3,0,1] row_mask:0xf bank_mask:0xf
	v_cndmask_b32_dpp v163, v207, v199, vcc quad_perm:[2,3,0,1] row_mask:0xf bank_mask:0xf
	v_cndmask_b32_dpp v164, v208, v200, vcc quad_perm:[2,3,0,1] row_mask:0xf bank_mask:0xf
	v_cndmask_b32_dpp v165, v209, v201, vcc quad_perm:[2,3,0,1] row_mask:0xf bank_mask:0xf
	v_cndmask_b32_dpp v166, v210, v202, vcc quad_perm:[2,3,0,1] row_mask:0xf bank_mask:0xf
	v_cndmask_b32_dpp v167, v211, v203, vcc quad_perm:[2,3,0,1] row_mask:0xf bank_mask:0xf
	s_mov_b64 vcc, s[98:99]
	s_nop 1
	v_cndmask_b32_dpp v180, v160, v164, vcc quad_perm:[1,0,3,2] row_mask:0xf bank_mask:0xf
	v_cndmask_b32_dpp v181, v161, v165, vcc quad_perm:[1,0,3,2] row_mask:0xf bank_mask:0xf
	v_cndmask_b32_dpp v182, v162, v166, vcc quad_perm:[1,0,3,2] row_mask:0xf bank_mask:0xf
	v_cndmask_b32_dpp v183, v163, v167, vcc quad_perm:[1,0,3,2] row_mask:0xf bank_mask:0xf
	v_cndmask_b32_dpp v188, v168, v172, vcc quad_perm:[1,0,3,2] row_mask:0xf bank_mask:0xf
	v_cndmask_b32_dpp v189, v169, v173, vcc quad_perm:[1,0,3,2] row_mask:0xf bank_mask:0xf
	v_cndmask_b32_dpp v190, v170, v174, vcc quad_perm:[1,0,3,2] row_mask:0xf bank_mask:0xf
	v_cndmask_b32_dpp v191, v171, v175, vcc quad_perm:[1,0,3,2] row_mask:0xf bank_mask:0xf
	s_not_b64 vcc, s[98:99]
	s_nop 1
	v_cndmask_b32_dpp v176, v164, v160, vcc quad_perm:[1,0,3,2] row_mask:0xf bank_mask:0xf
	v_cndmask_b32_dpp v177, v165, v161, vcc quad_perm:[1,0,3,2] row_mask:0xf bank_mask:0xf
	v_cndmask_b32_dpp v178, v166, v162, vcc quad_perm:[1,0,3,2] row_mask:0xf bank_mask:0xf
	v_cndmask_b32_dpp v179, v167, v163, vcc quad_perm:[1,0,3,2] row_mask:0xf bank_mask:0xf
	v_cndmask_b32_dpp v184, v172, v168, vcc quad_perm:[1,0,3,2] row_mask:0xf bank_mask:0xf
	v_cndmask_b32_dpp v185, v173, v169, vcc quad_perm:[1,0,3,2] row_mask:0xf bank_mask:0xf
	v_cndmask_b32_dpp v186, v174, v170, vcc quad_perm:[1,0,3,2] row_mask:0xf bank_mask:0xf
	v_cndmask_b32_dpp v187, v175, v171, vcc quad_perm:[1,0,3,2] row_mask:0xf bank_mask:0xf
	v_and_b32_e32 v192, 0x3c, v234
	v_and_b32_e32 v193, 3, v234
	v_lshlrev_b32_e32 v194, s28, v192
	v_lshl_add_u32 v194, v193, 4, v194
	v_mov_b32_e32 v195, 0
	s_lshl_b32 s98, 1, s28
	s_mov_b32 s99, 0
	v_lshl_add_u64 v[194:195], s[26:27], 0, v[194:195]
	global_store_dwordx4 v[194:195], v[176:179], off
	v_lshl_add_u64 v[194:195], v[194:195], 0, s[98:99]
	global_store_dwordx4 v[194:195], v[180:183], off
	v_lshl_add_u64 v[194:195], v[194:195], 0, s[98:99]
	global_store_dwordx4 v[194:195], v[184:187], off
	v_lshl_add_u64 v[194:195], v[194:195], 0, s[98:99]
	global_store_dwordx4 v[194:195], v[188:191], off
	s_mov_b32 s28, 0

.LBB0_900:
	s_cmpk_lt_i32 s25, 0x400
	s_cselect_b64 s[8:9], -1, 0
	s_and_b32 s26, s25, 0x3ff
	s_cmpk_gt_i32 s25, 0x3ff
	s_cselect_b64 s[6:7], -1, 0
	s_and_b64 s[12:13], s[6:7], exec
	s_movk_i32 s12, 0x148
	s_cselect_b32 s27, s12, 0x848
	s_movk_i32 s12, 0x290
	s_cselect_b32 s28, s12, 0x1090
	s_mov_b32 s12, 0x70500000
	s_cselect_b32 s30, s12, 0x6f400000
	s_lshr_b32 s16, s27, 3
	v_cmp_gt_i32_e32 vcc, s16, v22
	s_waitcnt vmcnt(0)
	s_barrier
	s_mov_b64 s[42:43], vcc
	s_and_saveexec_b64 s[12:13], vcc
	s_cbranch_execz .LBB0_903
	s_or_b32 s14, s4, s26
	s_add_u32 s15, s2, s30
	s_mul_i32 s21, s5, s28
	s_mul_hi_u32 s29, s14, s28
	s_addc_u32 s20, s3, 0
	s_add_i32 s29, s29, s21
	s_mul_i32 s14, s14, s28
	s_add_u32 s14, s15, s14
	s_addc_u32 s15, s20, s29
	v_mov_b32_e32 v2, v32
	v_ashrrev_i32_e32 v3, 31, v2
	v_lshl_add_u64 v[6:7], v[2:3], 1, s[14:15]
	global_load_dwordx4 v[118:121], v[6:7], off
.LBB0_903:
	s_or_b64 exec, exec, s[12:13]
	s_mov_b64 s[44:45], 0
	s_and_b32 s16, s24, 0x3ff
	s_lshl_b32 s29, s27, 1
	v_cmp_gt_i32_e32 vcc, s27, v22
	s_and_saveexec_b64 s[12:13], vcc
	s_cbranch_execz .LBB0_908
	v_readlane_b32 s14, v254, 33
	v_readlane_b32 s15, v254, 34
	s_add_u32 s14, s14, s16
	s_addc_u32 s15, s15, 0
	s_mul_i32 s15, s28, s15
	s_mul_hi_u32 s20, s28, s14
	s_add_i32 s31, s27, -1
	s_add_i32 s20, s20, s15
	s_mul_i32 s28, s28, s14
	s_add_u32 s14, s30, s28
	s_addc_u32 s15, 0, s20
	v_lshl_add_u64 v[2:3], v[24:25], 0, s[14:15]
	v_add_u32_e32 v0, s29, v23
	s_mov_b64 s[44:45], exec
	s_mov_b32 s51, s27
	v_mov_b32_e32 v138, v0
	s_mov_b64 s[20:21], 0x400
	v_mov_b32_e32 v100, 0
	v_mov_b32_e32 v101, 0
	v_mov_b32_e32 v102, 0
	v_mov_b32_e32 v103, 0
	v_mov_b32_e32 v104, 0
	v_lshl_add_u64 v[124:125], v[2:3], 0, s[20:21]
	v_lshl_add_u64 v[126:127], v[124:125], 0, s[20:21]
	v_lshl_add_u64 v[130:131], v[126:127], 0, s[20:21]
	v_lshl_add_u64 v[132:133], v[130:131], 0, s[20:21]
	v_add_u32_e32 v134, 0x200, v22
	v_add_u32_e32 v135, 0x400, v22
	v_add_u32_e32 v136, 0x600, v22
	v_add_u32_e32 v137, 0x800, v22
	v_cmpx_gt_i32_e32 vcc, s31, v22
	s_nop 1
	global_load_ushort v100, v[2:3], off
	v_cmpx_gt_i32_e32 vcc, s31, v134
	s_nop 1
	global_load_ushort v101, v[124:125], off
	v_cmpx_gt_i32_e32 vcc, s31, v135
	s_nop 1
	global_load_ushort v102, v[126:127], off
	v_cmpx_gt_i32_e32 vcc, s31, v136
	s_nop 1
	global_load_ushort v103, v[130:131], off
	v_cmpx_gt_i32_e32 vcc, s31, v137
	s_nop 1
	global_load_ushort v104, v[132:133], off
.LBB0_908:
	s_or_b64 exec, exec, s[12:13]
	s_and_b64 s[12:13], s[6:7], exec
	s_movk_i32 s12, 0x800
	s_cselect_b32 s30, 0x100, s12
	s_lshl_b32 s34, s30, 1
	s_add_i32 s31, s34, 0x380
	s_lshl_b32 s28, s27, 2
	s_and_b64 s[12:13], s[6:7], exec
	s_cselect_b32 s27, 0, 0x2000
	s_lshr_b32 s35, s30, 3
	s_and_b64 s[12:13], s[6:7], exec
	s_cselect_b32 s12, 5, 2
	s_lshl_b32 s36, s35, s12
	v_cmp_gt_i32_e32 vcc, s36, v22
	s_and_saveexec_b64 s[12:13], vcc
	s_cbranch_execz .LBB0_911
	v_cvt_f32_u32_e32 v0, s35
	s_and_b64 s[14:15], s[6:7], exec
	s_cselect_b32 s37, 5, 8
	s_lshl_b32 s14, s26, 15
	v_rcp_iflag_f32_e32 v0, v0
	s_add_u32 s14, s10, s14
	s_addc_u32 s15, s11, 0
	s_lshl_b32 s20, s27, 1
	v_mul_f32_e32 v0, 0x4f7ffffe, v0
	s_add_u32 s14, s14, s20
	v_cvt_u32_f32_e32 v0, v0
	s_addc_u32 s15, s15, 0
	s_and_b64 s[20:21], s[6:7], exec
	s_cselect_b32 s38, 8, 11
	s_sub_i32 s20, 0, s35
	v_mul_lo_u32 v2, s20, v0
	v_mul_hi_u32 v2, v0, v2
	v_add_u32_e32 v0, v0, v2
	v_add_u32_e32 v2, s28, v33
	s_mov_b64 s[20:21], 0
	v_mov_b32_e32 v3, v32
	v_mov_b32_e32 v4, v22
	v_sub_u32_e32 v6, 0, v4
	v_max_i32_e32 v6, v4, v6
	v_mul_hi_u32 v7, v6, v0
	v_mul_lo_u32 v8, v7, s35
	v_sub_u32_e32 v6, v6, v8
	v_add_u32_e32 v9, 1, v7
	v_cmp_le_u32_e32 vcc, s35, v6
	v_subrev_u32_e32 v8, s35, v6
	v_ashrrev_i32_e32 v5, 31, v4
	v_cndmask_b32_e32 v7, v7, v9, vcc
	v_cndmask_b32_e32 v6, v6, v8, vcc
	v_add_u32_e32 v8, 1, v7
	v_cmp_le_u32_e32 vcc, s35, v6
	v_add_u32_e32 v4, 0x200, v4
	s_nop 0
	v_cndmask_b32_e32 v6, v7, v8, vcc
	v_xor_b32_e32 v6, v6, v5
	v_sub_u32_e32 v5, v6, v5
	v_lshlrev_b32_e32 v10, s37, v5
	v_lshlrev_b32_e32 v6, s38, v5
	v_lshlrev_b32_e32 v8, 3, v10
	v_ashrrev_i32_e32 v7, 31, v6
	v_sub_u32_e32 v8, v3, v8
	v_lshl_add_u64 v[6:7], v[6:7], 1, s[14:15]
	v_ashrrev_i32_e32 v9, 31, v8
	v_lshl_add_u64 v[6:7], v[8:9], 1, v[6:7]
	global_load_dwordx4 v[142:145], v[6:7], off
	v_mul_lo_u32 v5, v5, s31
	v_lshlrev_b32_e32 v10, 4, v10
	v_sub_u32_e32 v5, v5, v10
	v_add_u32_e32 v3, 0x1000, v3
	v_add_u32_e32 v5, v2, v5
	v_add_u32_e32 v2, 0x2000, v2
	v_mov_b32_e32 v139, v5
	v_sub_u32_e32 v6, 0, v4
	v_max_i32_e32 v6, v4, v6
	v_mul_hi_u32 v7, v6, v0
	v_mul_lo_u32 v8, v7, s35
	v_sub_u32_e32 v6, v6, v8
	v_add_u32_e32 v9, 1, v7
	v_cmp_le_u32_e32 vcc, s35, v6
	v_subrev_u32_e32 v8, s35, v6
	v_ashrrev_i32_e32 v5, 31, v4
	v_cndmask_b32_e32 v7, v7, v9, vcc
	v_cndmask_b32_e32 v6, v6, v8, vcc
	v_add_u32_e32 v8, 1, v7
	v_cmp_le_u32_e32 vcc, s35, v6
	v_add_u32_e32 v4, 0x200, v4
	s_nop 0
	v_cndmask_b32_e32 v6, v7, v8, vcc
	v_xor_b32_e32 v6, v6, v5
	v_sub_u32_e32 v5, v6, v5
	v_lshlrev_b32_e32 v10, s37, v5
	v_lshlrev_b32_e32 v6, s38, v5
	v_lshlrev_b32_e32 v8, 3, v10
	v_ashrrev_i32_e32 v7, 31, v6
	v_sub_u32_e32 v8, v3, v8
	v_lshl_add_u64 v[6:7], v[6:7], 1, s[14:15]
	v_ashrrev_i32_e32 v9, 31, v8
	v_lshl_add_u64 v[6:7], v[8:9], 1, v[6:7]
	global_load_dwordx4 v[146:149], v[6:7], off
	v_mul_lo_u32 v5, v5, s31
	v_lshlrev_b32_e32 v10, 4, v10
	v_sub_u32_e32 v5, v5, v10
	v_add_u32_e32 v3, 0x1000, v3
	v_add_u32_e32 v5, v2, v5
	v_add_u32_e32 v2, 0x2000, v2
	v_mov_b32_e32 v140, v5
.LBB0_911:
	s_or_b64 exec, exec, s[12:13]
	s_waitcnt vmcnt(0)
	ds_write_b128 v139, v[142:145]
	ds_write_b128 v140, v[146:149]
	s_mov_b64 exec, s[42:43]
	ds_write_b128 v31, v[118:121]
	s_mov_b64 exec, s[44:45]
	ds_write_b16 v138, v100
	v_cmpx_gt_i32_e32 vcc, s51, v134
	s_nop 1
	ds_write_b16 v138, v101 offset:1024
	v_cmpx_gt_i32_e32 vcc, s51, v135
	s_nop 1
	ds_write_b16 v138, v102 offset:2048
	v_cmpx_gt_i32_e32 vcc, s51, v136
	s_nop 1
	ds_write_b16 v138, v103 offset:3072
	v_cmpx_gt_i32_e32 vcc, s51, v137
	s_nop 1
	ds_write_b16 v138, v104 offset:4096
	s_mov_b64 exec, -1
	s_and_b64 vcc, exec, s[8:9]
	s_cbranch_vccz .LBB0_916
	s_and_saveexec_b64 s[8:9], s[0:1]
	s_cbranch_execz .LBB0_915
	v_add_u32_e32 v2, s28, v31
	s_mov_b64 s[12:13], 0
	v_mov_b32_e32 v0, v22

.LBB0_917:
	s_and_b64 s[40:41], s[6:7], exec
	s_cselect_b32 s40, 0x400, 0
	v_readlane_b32 s42, v254, 29
	v_readlane_b32 s43, v254, 30
	s_nop 0
	s_add_u32 s40, s42, s40
	s_addc_u32 s41, s43, 0
	s_add_u32 s40, s40, s16
	s_addc_u32 s41, s41, 0
	s_lshl_b64 s[40:41], s[40:41], 7
	s_add_u32 s40, s2, s40
	s_addc_u32 s41, s3, s41
	v_mov_b32_e32 v98, 0x100000
	global_load_dwordx4 v[66:69], v98, s[40:41]
	global_load_dwordx4 v[70:73], v98, s[40:41] offset:16
	global_load_dwordx4 v[74:77], v98, s[40:41] offset:32
	global_load_dwordx4 v[78:81], v98, s[40:41] offset:48
	global_load_dwordx4 v[82:85], v98, s[40:41] offset:64
	global_load_dwordx4 v[86:89], v98, s[40:41] offset:80
	global_load_dwordx4 v[90:93], v98, s[40:41] offset:96
	global_load_dwordx4 v[94:97], v98, s[40:41] offset:112
	v_lshrrev_b32_e32 v2, s12, v29
	s_add_i32 s12, s13, s14
	s_lshr_b32 s13, s30, 6
	s_sub_i32 s15, 0, s13
	s_max_i32 s12, s12, s15
	v_and_b32_e32 v0, s9, v27
	s_min_i32 s8, s8, s13
	v_mov_b32_e32 v17, 0
	v_add_u32_e32 v19, s14, v2
	v_mul_u32_u24_e32 v18, s31, v0
	s_cmp_gt_i32 s12, s8
	v_mov_b32_e32 v16, v17
	v_mov_b32_e32 v15, v17
	v_mov_b32_e32 v14, v17
	v_mov_b32_e32 v13, v17
	v_mov_b32_e32 v12, v17
	v_mov_b32_e32 v11, v17
	v_mov_b32_e32 v10, v17
	v_mov_b32_e32 v9, v17
	v_mov_b32_e32 v8, v17
	v_mov_b32_e32 v7, v17
	v_mov_b32_e32 v6, v17
	v_mov_b32_e32 v5, v17
	v_mov_b32_e32 v4, v17
	v_mov_b32_e32 v3, v17
	v_mov_b32_e32 v2, v17
	s_waitcnt lgkmcnt(0)
	s_barrier
	s_cbranch_scc1 .LBB0_920
	v_subrev_u32_e32 v2, s12, v19
	s_lshr_b32 s13, s30, 1
	v_lshl_add_u32 v2, v2, 6, v18
	v_add3_u32 v20, v2, s28, v34
	v_add_u32_e32 v2, s13, v36
	s_lshl_b32 s13, s12, 5
	v_subrev_u32_e32 v21, s13, v2
	v_and_b32_e32 v2, 1, v21
	v_add_lshl_u32 v2, v29, v2, 1
	s_add_i32 s9, s12, -1
	v_sub_u32_e32 v2, s30, v2
	s_lshl_b32 s12, s12, 6
	v_subrev_u32_e32 v2, s12, v2
	v_add_u32_e32 v26, v35, v2
	v_mov_b32_e32 v2, 0
	v_mov_b32_e32 v3, v2
	v_mov_b32_e32 v4, v2
	v_mov_b32_e32 v5, v2
	v_mov_b32_e32 v6, v2
	v_mov_b32_e32 v7, v2
	v_mov_b32_e32 v8, v2
	v_mov_b32_e32 v9, v2
	v_mov_b32_e32 v10, v2
	v_mov_b32_e32 v11, v2
	v_mov_b32_e32 v12, v2
	v_mov_b32_e32 v13, v2
	v_mov_b32_e32 v14, v2
	v_mov_b32_e32 v15, v2
	v_mov_b32_e32 v16, v2
	v_mov_b32_e32 v17, v2
	v_and_b32_e32 v28, 1, v21
	v_mad_u32_u24 v28, v28, s29, v26
	ds_read2_b32 v[38:39], v28 offset1:1
	ds_read2_b32 v[40:41], v28 offset0:2 offset1:3
	ds_read_b128 v[42:45], v20
	ds_read2_b32 v[46:47], v28 offset0:8 offset1:9
	ds_read2_b32 v[48:49], v28 offset0:10 offset1:11
	ds_read_b128 v[146:149], v20 offset:32
	v_subrev_u32_e32 v21, 32, v21
	v_subrev_u32_e32 v20, 64, v20
	v_subrev_u32_e32 v26, 64, v26
.Lcv_loopA:
	s_add_i32 s9, s9, 1
	s_cmp_lt_i32 s9, s8
	s_cbranch_scc0 .Lcv_lastA
	v_and_b32_e32 v120, 1, v21
	v_mad_u32_u24 v120, v120, s29, v26
	ds_read2_b32 v[130:131], v120 offset1:1
	ds_read2_b32 v[132:133], v120 offset0:2 offset1:3
	ds_read_b128 v[134:137], v20
	ds_read2_b32 v[138:139], v120 offset0:8 offset1:9
	ds_read2_b32 v[140:141], v120 offset0:10 offset1:11
	ds_read_b128 v[142:145], v20 offset:32
	v_subrev_u32_e32 v21, 32, v21
	v_subrev_u32_e32 v20, 64, v20
	v_subrev_u32_e32 v26, 64, v26
	s_waitcnt lgkmcnt(6)
	v_mfma_f32_32x32x16_bf16 v[2:17], v[38:41], v[42:45], v[2:17]
	v_mfma_f32_32x32x16_bf16 v[2:17], v[46:49], v[146:149], v[2:17]
	s_add_i32 s9, s9, 1
	s_cmp_lt_i32 s9, s8
	s_cbranch_scc0 .Lcv_lastB
	v_and_b32_e32 v28, 1, v21
	v_mad_u32_u24 v28, v28, s29, v26
	ds_read2_b32 v[38:39], v28 offset1:1
	ds_read2_b32 v[40:41], v28 offset0:2 offset1:3
	ds_read_b128 v[42:45], v20
	ds_read2_b32 v[46:47], v28 offset0:8 offset1:9
	ds_read2_b32 v[48:49], v28 offset0:10 offset1:11
	ds_read_b128 v[146:149], v20 offset:32
	v_subrev_u32_e32 v21, 32, v21
	v_subrev_u32_e32 v20, 64, v20
	v_subrev_u32_e32 v26, 64, v26
	s_waitcnt lgkmcnt(6)
	v_mfma_f32_32x32x16_bf16 v[2:17], v[130:133], v[134:137], v[2:17]
	v_mfma_f32_32x32x16_bf16 v[2:17], v[138:141], v[142:145], v[2:17]
	s_branch .Lcv_loopA
.Lcv_lastA:
	s_waitcnt lgkmcnt(0)
	v_mfma_f32_32x32x16_bf16 v[2:17], v[38:41], v[42:45], v[2:17]
	v_mfma_f32_32x32x16_bf16 v[2:17], v[46:49], v[146:149], v[2:17]
	s_branch .Lcv_mm_done
.Lcv_lastB:
	s_waitcnt lgkmcnt(0)
	v_mfma_f32_32x32x16_bf16 v[2:17], v[130:133], v[134:137], v[2:17]
	v_mfma_f32_32x32x16_bf16 v[2:17], v[138:141], v[142:145], v[2:17]
.Lcv_mm_done:
.LBB0_920:
	v_mov_b32_e32 v20, 0
	s_movk_i32 s29, 0x7c00
	s_waitcnt vmcnt(0)
	v_add_f32_e32 v20, v20, v66
	v_add_f32_e32 v20, v20, v67
	v_add_f32_e32 v20, v20, v68
	v_add_f32_e32 v20, v20, v69
	v_add_f32_e32 v20, v20, v70
	v_add_f32_e32 v20, v20, v71
	v_add_f32_e32 v20, v20, v72
	v_add_f32_e32 v20, v20, v73
	v_add_f32_e32 v20, v20, v74
	v_add_f32_e32 v20, v20, v75
	v_add_f32_e32 v20, v20, v76
	v_add_f32_e32 v20, v20, v77
	v_add_f32_e32 v20, v20, v78
	v_add_f32_e32 v20, v20, v79
	v_add_f32_e32 v20, v20, v80
	v_add_f32_e32 v20, v20, v81
	v_add_f32_e32 v20, v20, v82
	v_add_f32_e32 v20, v20, v83
	v_add_f32_e32 v20, v20, v84
	v_add_f32_e32 v20, v20, v85
	v_add_f32_e32 v20, v20, v86
	v_add_f32_e32 v20, v20, v87
	v_add_f32_e32 v20, v20, v88
	v_add_f32_e32 v20, v20, v89
	v_add_f32_e32 v20, v20, v90
	v_add_f32_e32 v20, v20, v91
	v_add_f32_e32 v20, v20, v92
	v_add_f32_e32 v20, v20, v93
	v_add_f32_e32 v20, v20, v94
	v_add_f32_e32 v20, v20, v95
	v_add_f32_e32 v20, v20, v96
	v_add_f32_e32 v20, v20, v97
	v_add_f32_e32 v20, 0x358637bd, v20
	v_div_scale_f32 v21, s[8:9], v20, v20, 1.0
	v_rcp_f32_e32 v26, v21
	s_or_b32 s16, s26, s22
	s_add_i32 s12, s28, 0
	s_lshl_b64 s[8:9], s[16:17], 2
	v_fma_f32 v28, -v21, v26, 1.0
	v_fmac_f32_e32 v26, v28, v26
	v_div_scale_f32 v28, vcc, 1.0, v20, 1.0
	v_mul_f32_e32 v37, v28, v26
	v_fma_f32 v38, -v21, v37, v28
	v_fmac_f32_e32 v37, v38, v26
	v_fma_f32 v21, -v21, v37, v28
	v_div_fmas_f32 v21, v21, v26, v37
	v_div_fixup_f32 v26, v21, v20, 1.0
	v_mov_b32_e32 v20, s39
	ds_read_b64 v[20:21], v20
	v_lshl_add_u32 v42, v19, 5, v30
	v_ashrrev_i32_e32 v43, 31, v42
	s_waitcnt lgkmcnt(0)
	v_readfirstlane_b32 s13, v20
	v_readfirstlane_b32 s14, v21
	s_add_u32 s8, s13, s8
	s_addc_u32 s9, s14, s9
	global_load_dword v28, v1, s[8:9]
	s_lshl_b32 s8, s26, 15
	s_add_u32 s8, s10, s8
	s_addc_u32 s9, s11, 0
	s_lshl_b32 s13, s27, 1
	s_add_u32 s8, s8, s13
	s_addc_u32 s9, s9, 0
	s_and_b64 s[6:7], s[6:7], exec
	s_cselect_b32 s6, 8, 11
	v_lshlrev_b32_e32 v0, s6, v0
	v_lshlrev_b32_e32 v0, 1, v0
	v_lshl_add_u64 v[44:45], s[8:9], 0, v[0:1]
	v_lshlrev_b32_e32 v0, 1, v42
	v_add3_u32 v0, s12, v18, v0
	s_barrier
	ds_read2_b64 v[38:41], v0 offset0:56 offset1:58
	ds_read2_b64 v[18:21], v0 offset0:60 offset1:62
	v_readlane_b32 s6, v253, 8
	s_add_i32 s25, s25, s6
	s_add_i32 s24, s24, s6
	s_waitcnt lgkmcnt(1)
	v_and_b32_e32 v47, 0xffff0000, v38
	v_lshlrev_b32_e32 v46, 16, v38
	s_cmpk_gt_i32 s25, 0x7ff
	s_waitcnt vmcnt(0)
	v_pk_mul_f32 v[46:47], v[28:29], v[46:47] op_sel_hi:[0,1]
	v_pk_fma_f32 v[2:3], v[2:3], v[26:27], v[46:47] op_sel_hi:[1,0,1]
	v_and_b32_e32 v47, 0xffff0000, v39
	v_lshlrev_b32_e32 v46, 16, v39
	v_pk_mul_f32 v[38:39], v[28:29], v[46:47] op_sel_hi:[0,1]
	v_pk_fma_f32 v[4:5], v[4:5], v[26:27], v[38:39] op_sel_hi:[1,0,1]
	v_cvt_pk_bf16_f32 v2, v2, v3
	v_cvt_pk_bf16_f32 v3, v4, v5
	v_lshl_add_u64 v[4:5], v[42:43], 1, v[44:45]
	global_store_dwordx2 v[4:5], v[2:3], off
	v_and_b32_e32 v3, 0xffff0000, v40
	v_lshlrev_b32_e32 v2, 16, v40
	v_pk_mul_f32 v[2:3], v[28:29], v[2:3] op_sel_hi:[0,1]
	v_pk_fma_f32 v[2:3], v[6:7], v[26:27], v[2:3] op_sel_hi:[1,0,1]
	v_and_b32_e32 v7, 0xffff0000, v41
	v_lshlrev_b32_e32 v6, 16, v41
	v_pk_mul_f32 v[6:7], v[28:29], v[6:7] op_sel_hi:[0,1]
	v_pk_fma_f32 v[6:7], v[8:9], v[26:27], v[6:7] op_sel_hi:[1,0,1]
	v_cvt_pk_bf16_f32 v2, v2, v3
	v_cvt_pk_bf16_f32 v3, v6, v7
	global_store_dwordx2 v[4:5], v[2:3], off offset:16
	s_waitcnt lgkmcnt(0)
	v_and_b32_e32 v3, 0xffff0000, v18
	v_lshlrev_b32_e32 v2, 16, v18
	v_and_b32_e32 v7, 0xffff0000, v19
	v_lshlrev_b32_e32 v6, 16, v19
	v_pk_mul_f32 v[2:3], v[28:29], v[2:3] op_sel_hi:[0,1]
	v_pk_mul_f32 v[6:7], v[28:29], v[6:7] op_sel_hi:[0,1]
	v_pk_fma_f32 v[2:3], v[10:11], v[26:27], v[2:3] op_sel_hi:[1,0,1]
	v_pk_fma_f32 v[6:7], v[12:13], v[26:27], v[6:7] op_sel_hi:[1,0,1]
	v_cvt_pk_bf16_f32 v2, v2, v3
	v_cvt_pk_bf16_f32 v3, v6, v7
	global_store_dwordx2 v[4:5], v[2:3], off offset:32
	v_and_b32_e32 v3, 0xffff0000, v20
	v_lshlrev_b32_e32 v2, 16, v20
	v_and_b32_e32 v7, 0xffff0000, v21
	v_lshlrev_b32_e32 v6, 16, v21
	v_pk_mul_f32 v[2:3], v[28:29], v[2:3] op_sel_hi:[0,1]
	v_pk_mul_f32 v[6:7], v[28:29], v[6:7] op_sel_hi:[0,1]
	v_pk_fma_f32 v[2:3], v[14:15], v[26:27], v[2:3] op_sel_hi:[1,0,1]
	v_pk_fma_f32 v[6:7], v[16:17], v[26:27], v[6:7] op_sel_hi:[1,0,1]
	v_cvt_pk_bf16_f32 v2, v2, v3
	v_cvt_pk_bf16_f32 v3, v6, v7
	global_store_dwordx2 v[4:5], v[2:3], off offset:48
	s_cbranch_scc0 .LBB0_900

.LBB0_982:
	s_and_b64 s[12:13], s[8:9], exec
	s_cselect_b32 s11, 64, 8
	s_lshl_b32 s12, s6, 11
	s_addk_i32 s12, 0x2000
	s_lshl_b32 s13, s6, 8
	s_and_b64 s[8:9], s[8:9], exec
	s_cselect_b32 s12, s12, s13
	s_ashr_i32 s13, s12, 5
	s_add_i32 s14, s11, -1
	s_cmp_eq_u32 s16, 0
	s_cselect_b64 s[92:93], -1, 0
	v_mov_b32_e32 v35, v234
	s_and_b64 s[8:9], s[92:93], exec
	s_mov_b32 s4, s6
	s_cselect_b32 s8, 0, s14
	v_ashrrev_i32_e32 v0, 3, v35
	v_writelane_b32 v255, s4, 62
	v_sub_u32_e32 v34, 31, v0
	s_add_i32 s8, s13, s8
	v_writelane_b32 v255, s5, 63
	v_cndmask_b32_e64 v38, v34, v0, s[92:93]
	s_lshl_b32 s9, s8, 5
	s_lshl_b32 s14, s16, 8
	s_lshl_b32 s16, s16, 9
	v_readlane_b32 s4, v255, 13
	v_add_u32_e32 v38, s9, v38
	s_add_u32 s94, s4, s16
	v_readlane_b32 s4, v255, 14
	v_lshlrev_b32_e32 v42, 4, v35
	v_ashrrev_i32_e32 v39, 31, v38
	s_addc_u32 s95, s4, 0
	v_and_b32_e32 v0, 0x70, v42
	v_lshlrev_b64 v[38:39], 4, v[38:39]
	v_lshl_add_u64 v[36:37], s[94:95], 0, v[0:1]
	v_or_b32_e32 v0, s26, v38
	s_sub_u32 s96, 0, s14
	v_mad_u64_u32 v[40:41], s[14:15], v0, s33, v[36:37]
	v_mad_i32_i24 v41, v39, s33, v41
	s_mov_b32 m0, s22
	s_nop 0
	global_load_lds_dwordx4 v[40:41], off
	s_mov_b64 s[4:5], 0x80
	v_lshl_add_u64 v[38:39], v[40:41], 0, s[4:5]
	s_mov_b32 m0, s19
	s_nop 0
	global_load_lds_dwordx4 v[38:39], off
	s_mov_b32 s20, s19
	s_mov_b64 s[18:19], 0x100
	v_lshl_add_u64 v[38:39], v[40:41], 0, s[18:19]
	s_mov_b64 s[24:25], 0x180
	v_readlane_b32 s6, v255, 4
	s_mov_b32 m0, s6
	s_nop 0
	global_load_lds_dwordx4 v[38:39], off
	v_lshl_add_u64 v[38:39], v[40:41], 0, s[24:25]
	v_readlane_b32 s6, v255, 5
	s_mov_b32 m0, s6
	s_nop 0
	global_load_lds_dwordx4 v[38:39], off
	v_subrev_co_u32_e32 v38, vcc, s16, v40
	s_mov_b64 s[6:7], 0x400
	s_nop 0
	v_subbrev_co_u32_e32 v39, vcc, 0, v41, vcc
	v_add_u32_e32 v0, 64, v35
	v_lshl_add_u64 v[38:39], v[38:39], 0, s[6:7]
	v_ashrrev_i32_e32 v0, 3, v0
	v_readlane_b32 s15, v255, 9
	s_mov_b32 m0, s15
	s_nop 0
	global_load_lds_dwordx4 v[38:39], off
	v_sub_u32_e32 v38, 31, v0
	v_cndmask_b32_e64 v0, v38, v0, s[92:93]
	v_add_u32_e32 v38, s9, v0
	v_ashrrev_i32_e32 v39, 31, v38
	v_lshlrev_b64 v[38:39], 4, v[38:39]
	v_or_b32_e32 v0, s26, v38
	v_mad_u64_u32 v[40:41], s[14:15], v0, s33, v[36:37]
	v_mad_i32_i24 v41, v39, s33, v41
	v_readlane_b32 s15, v255, 2
	s_mov_b32 m0, s15
	s_nop 0
	global_load_lds_dwordx4 v[40:41], off
	v_lshl_add_u64 v[38:39], v[40:41], 0, s[4:5]
	v_readlane_b32 s15, v255, 3
	s_mov_b32 m0, s15
	s_nop 0
	global_load_lds_dwordx4 v[38:39], off
	v_lshl_add_u64 v[38:39], v[40:41], 0, s[18:19]
	v_readlane_b32 s15, v255, 41
	s_mov_b32 m0, s15
	s_nop 0
	global_load_lds_dwordx4 v[38:39], off
	v_lshl_add_u64 v[38:39], v[40:41], 0, s[24:25]
	v_readlane_b32 s15, v255, 42
	s_mov_b32 m0, s15
	s_nop 0
	global_load_lds_dwordx4 v[38:39], off
	v_subrev_co_u32_e32 v38, vcc, s16, v40
	v_add_u32_e32 v0, 0x80, v35
	s_nop 0
	v_subbrev_co_u32_e32 v39, vcc, 0, v41, vcc
	v_lshl_add_u64 v[38:39], v[38:39], 0, s[6:7]
	v_ashrrev_i32_e32 v0, 3, v0
	v_readlane_b32 s15, v255, 43
	s_mov_b32 m0, s15
	s_nop 0
	global_load_lds_dwordx4 v[38:39], off
	v_sub_u32_e32 v38, 31, v0
	v_cndmask_b32_e64 v0, v38, v0, s[92:93]
	v_add_u32_e32 v38, s9, v0
	v_ashrrev_i32_e32 v39, 31, v38
	v_lshlrev_b64 v[38:39], 4, v[38:39]
	v_or_b32_e32 v0, s26, v38
	v_mad_u64_u32 v[40:41], s[14:15], v0, s33, v[36:37]
	v_mad_i32_i24 v41, v39, s33, v41
	v_readlane_b32 s15, v255, 44
	s_mov_b32 m0, s15
	s_nop 0
	global_load_lds_dwordx4 v[40:41], off
	v_lshl_add_u64 v[38:39], v[40:41], 0, s[4:5]
	v_readlane_b32 s15, v255, 45
	s_mov_b32 m0, s15
	s_nop 0
	global_load_lds_dwordx4 v[38:39], off
	v_lshl_add_u64 v[38:39], v[40:41], 0, s[18:19]
	v_readlane_b32 s15, v255, 46
	s_mov_b32 m0, s15
	s_nop 0
	global_load_lds_dwordx4 v[38:39], off
	v_lshl_add_u64 v[38:39], v[40:41], 0, s[24:25]
	v_add_u32_e32 v0, 0xc0, v35
	v_readlane_b32 s15, v255, 47
	s_mov_b32 m0, s15
	s_nop 0
	global_load_lds_dwordx4 v[38:39], off
	v_subrev_co_u32_e32 v38, vcc, s16, v40
	v_ashrrev_i32_e32 v0, 3, v0
	v_lshlrev_b32_e32 v34, 3, v35
	v_subbrev_co_u32_e32 v39, vcc, 0, v41, vcc
	v_sub_u32_e32 v35, 31, v0
	v_lshl_add_u64 v[38:39], v[38:39], 0, s[6:7]
	v_cndmask_b32_e64 v0, v35, v0, s[92:93]
	v_readlane_b32 s15, v255, 48
	s_mov_b32 m0, s15
	s_nop 0
	global_load_lds_dwordx4 v[38:39], off
	v_add_u32_e32 v38, s9, v0
	v_ashrrev_i32_e32 v39, 31, v38
	v_lshlrev_b64 v[38:39], 4, v[38:39]
	v_or_b32_e32 v0, s26, v38
	v_mad_u64_u32 v[36:37], s[14:15], v0, s33, v[36:37]
	v_mad_i32_i24 v37, v39, s33, v37
	v_readlane_b32 s14, v255, 49
	s_mov_b32 m0, s14
	s_nop 0
	global_load_lds_dwordx4 v[36:37], off
	v_lshl_add_u64 v[38:39], v[36:37], 0, s[4:5]
	v_readlane_b32 s4, v255, 50
	s_mov_b32 m0, s4
	s_nop 0
	global_load_lds_dwordx4 v[38:39], off
	v_lshl_add_u64 v[38:39], v[36:37], 0, s[18:19]
	v_readlane_b32 s4, v255, 51
	s_mov_b32 m0, s4
	s_nop 0
	global_load_lds_dwordx4 v[38:39], off
	v_lshl_add_u64 v[38:39], v[36:37], 0, s[24:25]
	v_subrev_co_u32_e32 v36, vcc, s16, v36
	v_readlane_b32 s4, v255, 52
	s_mov_b32 m0, s4
	s_nop 0
	global_load_lds_dwordx4 v[38:39], off
	s_nop 0
	v_subbrev_co_u32_e32 v37, vcc, 0, v37, vcc
	v_lshl_add_u64 v[36:37], v[36:37], 0, s[6:7]
	v_readlane_b32 s4, v255, 53
	s_mov_b32 m0, s4
	s_nop 0
	global_load_lds_dwordx4 v[36:37], off
	s_subb_u32 s97, 0, 0
	s_ashr_i32 s9, s8, 31
	v_readlane_b32 s24, v255, 59
	s_lshl_b64 s[8:9], s[8:9], 5
	s_lshl_b32 s16, s24, 4
	s_or_b32 s8, s8, s16
	s_or_b32 s8, s8, s26
	s_lshl_b64 s[14:15], s[8:9], 11
	v_readlane_b32 s4, v255, 6
	s_add_u32 s14, s4, s14
	v_readlane_b32 s4, v255, 0
	s_addc_u32 s15, s4, s15
	v_ashrrev_i32_e32 v35, 31, v34
	s_lshl_b64 s[8:9], s[8:9], 8
	v_lshl_add_u64 v[34:35], v[34:35], 1, s[14:15]
	v_readlane_b32 s4, v255, 10
	s_mov_b32 m0, s4
	s_nop 0
	global_load_lds_dwordx4 v[34:35], off
	s_add_u32 s8, s27, s8
	v_lshl_add_u64 v[34:35], v[34:35], 0, s[6:7]
	v_readlane_b32 s4, v255, 54
	s_mov_b32 m0, s4
	s_nop 0
	global_load_lds_dwordx4 v[34:35], off
	s_addc_u32 s9, s23, s9
	v_and_b32_e32 v0, 0xf0, v42
	v_lshl_add_u64 v[34:35], s[8:9], 0, v[0:1]
	v_readlane_b32 s4, v255, 11
	s_mov_b32 m0, s4
	s_nop 0
	global_load_lds_dwordx4 v[34:35], off
	s_lshl_b32 s14, s10, 6
	s_lshl_b32 s8, s24, 26
	v_readlane_b32 s4, v255, 15
	s_add_u32 s8, s4, s8
	v_readlane_b32 s4, v255, 16
	s_addc_u32 s9, s4, 0
	s_lshl_b32 s15, s26, 8
	s_add_u32 s8, s8, s15
	s_addc_u32 s9, s9, 0
	s_lshl_b32 s10, s10, 7
	s_add_u32 s8, s8, s10
	s_addc_u32 s9, s9, 0
	v_mov_b32_e32 v155, v1
	s_mov_b32 s21, 0
	s_mov_b32 s19, s20
	v_add_u32_e32 v157, s14, v176
	v_lshl_add_u64 v[158:159], s[8:9], 0, v[154:155]
	v_cndmask_b32_e64 v155, v177, v152, s[92:93]
	v_cndmask_b32_e64 v197, v178, v161, s[92:93]
	v_cndmask_b32_e64 v198, v179, v162, s[92:93]
	v_cndmask_b32_e64 v199, v180, v163, s[92:93]
	v_cndmask_b32_e64 v200, v181, v164, s[92:93]
	v_cndmask_b32_e64 v201, v182, v165, s[92:93]
	v_cndmask_b32_e64 v202, v183, v166, s[92:93]
	v_cndmask_b32_e64 v203, v184, v167, s[92:93]
	v_cndmask_b32_e64 v204, v185, v168, s[92:93]
	v_cndmask_b32_e64 v205, v186, v169, s[92:93]
	v_cndmask_b32_e64 v206, v187, v170, s[92:93]
	v_cndmask_b32_e64 v207, v188, v171, s[92:93]
	v_cndmask_b32_e64 v208, v189, v172, s[92:93]
	v_cndmask_b32_e64 v209, v190, v173, s[92:93]
	v_cndmask_b32_e64 v210, v191, v174, s[92:93]
	v_cndmask_b32_e64 v211, v192, v175, s[92:93]
	v_add_u32_e32 v212, s14, v193
	s_or_b32 s16, s26, s16
	s_add_i32 s20, s11, -3
	v_readlane_b32 s25, v255, 60
	s_waitcnt vmcnt(0)
	s_branch .LBB0_984

.LBB0_987:
	s_add_i32 s10, s21, 1
	s_cmp_ge_u32 s10, s11
	s_cbranch_scc1 .LBB0_989
	s_add_i32 s14, s20, 1
	s_and_b64 s[8:9], s[92:93], exec
	v_mov_b32_e32 v35, v234
	s_cselect_b32 s8, s10, s14
	s_add_i32 s8, s8, s13
	v_ashrrev_i32_e32 v0, 3, v35
	v_sub_u32_e32 v36, 31, v0
	s_lshl_b32 s9, s8, 5
	v_cndmask_b32_e64 v0, v36, v0, s[92:93]
	v_add_u32_e32 v36, s9, v0
	v_ashrrev_i32_e32 v37, 31, v36
	v_lshlrev_b64 v[36:37], 4, v[36:37]
	v_or_b32_e32 v0, s26, v36
	v_mov_b64_e32 v[38:39], s[94:95]
	v_mad_u64_u32 v[40:41], s[14:15], v0, s33, v[38:39]
	v_lshlrev_b32_e32 v42, 4, v35
	v_mad_i32_i24 v41, v37, s33, v41
	v_and_b32_e32 v0, 0x70, v42
	v_readlane_b32 s4, v255, 55
	v_lshl_add_u64 v[36:37], v[40:41], 0, v[0:1]
	s_mov_b32 m0, s4
	s_nop 0
	global_load_lds_dwordx4 v[36:37], off
	s_mov_b64 s[6:7], 0x80
	v_readlane_b32 s4, v255, 19
	v_lshl_add_u64 v[40:41], v[36:37], 0, s[6:7]
	s_mov_b32 m0, s4
	s_nop 0
	global_load_lds_dwordx4 v[40:41], off
	s_mov_b64 s[4:5], 0x100
	v_lshl_add_u64 v[40:41], v[36:37], 0, s[4:5]
	v_readlane_b32 s15, v255, 20
	s_mov_b32 m0, s15
	s_nop 0
	global_load_lds_dwordx4 v[40:41], off
	s_mov_b64 s[30:31], 0x180
	v_lshl_add_u64 v[40:41], v[36:37], 0, s[30:31]
	v_readlane_b32 s15, v255, 21
	s_mov_b32 m0, s15
	s_nop 0
	global_load_lds_dwordx4 v[40:41], off
	s_lshl_b64 s[14:15], s[96:97], 1
	s_mov_b64 s[24:25], 0x400
	v_lshl_add_u64 v[36:37], v[36:37], 0, s[14:15]
	v_lshl_add_u64 v[36:37], v[36:37], 0, s[24:25]
	v_readlane_b32 s28, v255, 22
	s_mov_b32 m0, s28
	s_nop 0
	global_load_lds_dwordx4 v[36:37], off
	v_add_u32_e32 v36, 64, v35
	v_ashrrev_i32_e32 v36, 3, v36
	v_sub_u32_e32 v37, 31, v36
	v_cndmask_b32_e64 v36, v37, v36, s[92:93]
	v_add_u32_e32 v36, s9, v36
	v_ashrrev_i32_e32 v37, 31, v36
	v_lshlrev_b64 v[36:37], 4, v[36:37]
	v_or_b32_e32 v36, s26, v36
	v_mad_u64_u32 v[40:41], vcc, v36, s33, v[38:39]
	v_mad_i32_i24 v41, v37, s33, v41
	v_lshl_add_u64 v[36:37], v[40:41], 0, v[0:1]
	v_readlane_b32 s28, v255, 23
	s_mov_b32 m0, s28
	s_nop 0
	global_load_lds_dwordx4 v[36:37], off
	v_lshl_add_u64 v[40:41], v[36:37], 0, s[6:7]
	v_readlane_b32 s28, v255, 24
	s_mov_b32 m0, s28
	s_nop 0
	global_load_lds_dwordx4 v[40:41], off
	v_lshl_add_u64 v[40:41], v[36:37], 0, s[4:5]
	v_readlane_b32 s28, v255, 25
	s_mov_b32 m0, s28
	s_nop 0
	global_load_lds_dwordx4 v[40:41], off
	v_lshl_add_u64 v[40:41], v[36:37], 0, s[30:31]
	v_lshl_add_u64 v[36:37], v[36:37], 0, s[14:15]
	v_readlane_b32 s28, v255, 26
	s_mov_b32 m0, s28
	s_nop 0
	global_load_lds_dwordx4 v[40:41], off
	v_lshl_add_u64 v[36:37], v[36:37], 0, s[24:25]
	v_readlane_b32 s28, v255, 27
	s_mov_b32 m0, s28
	s_nop 0
	global_load_lds_dwordx4 v[36:37], off
	v_add_u32_e32 v36, 0x80, v35
	v_ashrrev_i32_e32 v36, 3, v36
	v_sub_u32_e32 v37, 31, v36
	v_cndmask_b32_e64 v36, v37, v36, s[92:93]
	v_add_u32_e32 v36, s9, v36
	v_ashrrev_i32_e32 v37, 31, v36
	v_lshlrev_b64 v[36:37], 4, v[36:37]
	v_or_b32_e32 v36, s26, v36
	v_mad_u64_u32 v[40:41], vcc, v36, s33, v[38:39]
	v_mad_i32_i24 v41, v37, s33, v41
	v_lshl_add_u64 v[36:37], v[40:41], 0, v[0:1]
	v_readlane_b32 s28, v255, 28
	s_mov_b32 m0, s28
	s_nop 0
	global_load_lds_dwordx4 v[36:37], off
	v_lshl_add_u64 v[40:41], v[36:37], 0, s[6:7]
	v_readlane_b32 s28, v255, 29
	s_mov_b32 m0, s28
	s_nop 0
	global_load_lds_dwordx4 v[40:41], off
	v_lshl_add_u64 v[40:41], v[36:37], 0, s[4:5]
	v_lshlrev_b32_e32 v34, 3, v35
	v_readlane_b32 s28, v255, 30
	s_mov_b32 m0, s28
	s_nop 0
	global_load_lds_dwordx4 v[40:41], off
	v_lshl_add_u64 v[40:41], v[36:37], 0, s[30:31]
	v_lshl_add_u64 v[36:37], v[36:37], 0, s[14:15]
	v_add_u32_e32 v35, 0xc0, v35
	v_readlane_b32 s28, v255, 31
	s_mov_b32 m0, s28
	s_nop 0
	global_load_lds_dwordx4 v[40:41], off
	v_lshl_add_u64 v[36:37], v[36:37], 0, s[24:25]
	v_ashrrev_i32_e32 v35, 3, v35
	v_readlane_b32 s28, v255, 32
	s_mov_b32 m0, s28
	s_nop 0
	global_load_lds_dwordx4 v[36:37], off
	v_sub_u32_e32 v36, 31, v35
	v_cndmask_b32_e64 v35, v36, v35, s[92:93]
	v_add_u32_e32 v36, s9, v35
	v_ashrrev_i32_e32 v37, 31, v36
	v_lshlrev_b64 v[36:37], 4, v[36:37]
	v_or_b32_e32 v35, s26, v36
	v_mad_u64_u32 v[38:39], vcc, v35, s33, v[38:39]
	v_mad_i32_i24 v39, v37, s33, v39
	v_lshl_add_u64 v[36:37], v[38:39], 0, v[0:1]
	v_readlane_b32 s18, v255, 33
	s_mov_b32 m0, s18
	s_nop 0
	global_load_lds_dwordx4 v[36:37], off
	v_lshl_add_u64 v[38:39], v[36:37], 0, s[6:7]
	v_readlane_b32 s6, v255, 34
	s_mov_b32 m0, s6
	s_nop 0
	global_load_lds_dwordx4 v[38:39], off
	v_lshl_add_u64 v[38:39], v[36:37], 0, s[4:5]
	v_readlane_b32 s4, v255, 35
	s_mov_b32 m0, s4
	s_nop 0
	global_load_lds_dwordx4 v[38:39], off
	v_lshl_add_u64 v[38:39], v[36:37], 0, s[30:31]
	v_readlane_b32 s4, v255, 36
	s_mov_b32 m0, s4
	s_nop 0
	global_load_lds_dwordx4 v[38:39], off
	v_lshl_add_u64 v[36:37], v[36:37], 0, s[14:15]
	v_lshl_add_u64 v[36:37], v[36:37], 0, s[24:25]
	v_readlane_b32 s4, v255, 37
	s_mov_b32 m0, s4
	s_nop 0
	global_load_lds_dwordx4 v[36:37], off
	s_ashr_i32 s9, s8, 31
	s_lshl_b64 s[8:9], s[8:9], 5
	s_or_b64 s[8:9], s[8:9], s[16:17]
	s_lshl_b64 s[14:15], s[8:9], 11
	v_readlane_b32 s4, v255, 6
	s_add_u32 s14, s4, s14
	v_readlane_b32 s4, v255, 0
	s_addc_u32 s15, s4, s15
	v_ashrrev_i32_e32 v35, 31, v34
	s_lshl_b64 s[8:9], s[8:9], 8
	v_lshl_add_u64 v[34:35], v[34:35], 1, s[14:15]
	v_readlane_b32 s4, v255, 38
	s_mov_b32 m0, s4
	s_nop 0
	global_load_lds_dwordx4 v[34:35], off
	s_add_u32 s8, s27, s8
	v_lshl_add_u64 v[34:35], v[34:35], 0, s[24:25]
	v_readlane_b32 s4, v255, 39
	s_mov_b32 m0, s4
	s_nop 0
	global_load_lds_dwordx4 v[34:35], off
	s_addc_u32 s9, s23, s9
	v_and_b32_e32 v0, 0xf0, v42
	v_lshl_add_u64 v[34:35], s[8:9], 0, v[0:1]
	v_readlane_b32 s4, v255, 40
	s_mov_b32 m0, s4
	s_nop 0
	global_load_lds_dwordx4 v[34:35], off
.LBB0_989:
	ds_read_b128 v[66:69], v194 offset:8192
	ds_read_b128 v[34:37], v194
	ds_read_b128 v[38:41], v194 offset:32
	ds_read_b128 v[82:85], v194 offset:8224
	v_cvt_pk_bf16_f32 v214, v18, v19
	v_cvt_pk_bf16_f32 v215, v20, v21
	s_waitcnt lgkmcnt(2)
	v_mfma_f32_32x32x16_bf16 v[50:65], v[66:69], v[34:37], 0
	v_cvt_pk_bf16_f32 v216, v22, v23
	v_cvt_pk_bf16_f32 v217, v24, v25
	v_cvt_pk_bf16_f32 v228, v26, v27
	v_cvt_pk_bf16_f32 v229, v28, v29
	v_cvt_pk_bf16_f32 v230, v30, v31
	v_cvt_pk_bf16_f32 v231, v32, v33
	v_add_u32_e32 v106, 0x5000, v196
	s_waitcnt lgkmcnt(0)
	v_mfma_f32_32x32x16_bf16 v[50:65], v[82:85], v[38:41], v[50:65]
	ds_read_b128 v[86:89], v194 offset:8256
	ds_read_b128 v[34:37], v194 offset:64
	ds_read_b128 v[90:93], v194 offset:8288
	ds_read_b128 v[38:41], v194 offset:96
	s_add_i32 s14, s20, 2
	s_and_b64 s[8:9], s[92:93], exec
	s_cselect_b32 s8, s21, s14
	s_lshl_b32 s8, s8, 5
	s_add_i32 s8, s8, s12
	s_add_i32 s18, s21, 2
	s_waitcnt lgkmcnt(2)
	v_mfma_f32_32x32x16_bf16 v[50:65], v[86:89], v[34:37], v[50:65]
	ds_read_b128 v[34:37], v194 offset:4096
	ds_read_b128 v[70:73], v194 offset:12288
	ds_read_b128 v[74:77], v194 offset:4128
	ds_read_b128 v[94:97], v194 offset:12320
	s_cmp_ge_u32 s18, s11
	s_waitcnt lgkmcnt(4)
	v_mfma_f32_32x32x16_bf16 v[50:65], v[90:93], v[38:41], v[50:65]
	s_waitcnt lgkmcnt(2)
	v_mfma_f32_32x32x16_bf16 v[34:49], v[34:37], v[70:73], 0
	s_nop 9
	v_cndmask_b32_e64 v0, 0, v50, s[0:1]
	v_cndmask_b32_e64 v50, 0, v51, s[2:3]
	v_cndmask_b32_e64 v51, 0, v52, s[34:35]
	v_cndmask_b32_e64 v52, 0, v53, s[36:37]
	v_cndmask_b32_e64 v53, 0, v54, s[38:39]
	v_cndmask_b32_e64 v57, 0, v57, s[44:45]
	v_cvt_pk_bf16_f32 v54, v0, v50
	s_waitcnt lgkmcnt(0)
	v_mfma_f32_32x32x16_bf16 v[34:49], v[74:77], v[94:97], v[34:49]
	ds_read_b128 v[74:77], v194 offset:4160
	ds_read_b128 v[98:101], v194 offset:12352
	ds_read_b128 v[78:81], v194 offset:4192
	ds_read_b128 v[102:105], v194 offset:12384
	v_cndmask_b32_e64 v58, 0, v58, s[46:47]
	v_cndmask_b32_e64 v59, 0, v59, s[48:49]
	v_cndmask_b32_e64 v60, 0, v60, s[50:51]
	v_cndmask_b32_e64 v61, 0, v61, s[52:53]
	v_cndmask_b32_e64 v62, 0, v62, s[54:55]
	v_cndmask_b32_e64 v63, 0, v63, s[56:57]
	s_waitcnt lgkmcnt(2)
	v_mfma_f32_32x32x16_bf16 v[34:49], v[74:77], v[98:101], v[34:49]
	v_cndmask_b32_e64 v64, 0, v64, s[58:59]
	v_cndmask_b32_e64 v0, 0, v65, s[60:61]
	v_cvt_pk_bf16_f32 v58, v58, v59
	v_cvt_pk_bf16_f32 v59, v60, v61
	v_cvt_pk_bf16_f32 v60, v62, v63
	v_cvt_pk_bf16_f32 v61, v64, v0
	s_waitcnt lgkmcnt(0)
	v_mfma_f32_32x32x16_bf16 v[34:49], v[78:81], v[102:105], v[34:49]
	v_mfma_f32_32x32x16_bf16 v[66:81], v[66:69], v[70:73], 0
	s_nop 10
	v_cndmask_b32_e64 v34, v34, 0, s[62:63]
	v_cndmask_b32_e64 v35, 0, v35, s[0:1]
	v_cvt_pk_bf16_f32 v34, v34, v35
	v_cndmask_b32_e64 v42, v42, 0, s[76:77]
	v_cndmask_b32_e64 v43, v43, 0, s[78:79]
	v_cvt_pk_bf16_f32 v42, v42, v43
	v_cndmask_b32_e64 v43, v44, 0, s[80:81]
	v_mfma_f32_32x32x16_bf16 v[66:81], v[82:85], v[94:97], v[66:81]
	v_cndmask_b32_e64 v82, 0, v55, s[40:41]
	v_cndmask_b32_e64 v83, 0, v56, s[42:43]
	v_cvt_pk_bf16_f32 v55, v51, v52
	v_cvt_pk_bf16_f32 v56, v53, v82
	v_cvt_pk_bf16_f32 v57, v83, v57
	ds_read_b64_tr_b16 v[146:147], v157 offset:0x4000
	ds_read_b64_tr_b16 v[148:149], v157 offset:0x4000+1024
	ds_read_b64_tr_b16 v[134:135], v157 offset:0x4000+2048
	ds_read_b64_tr_b16 v[136:137], v157 offset:0x4000+3072
	ds_read_b64_tr_b16 v[126:127], v176 offset:0x1000
	ds_read_b64_tr_b16 v[128:129], v176 offset:0x1000+1024
	ds_read_b64_tr_b16 v[122:123], v176 offset:0x1000+2048
	ds_read_b64_tr_b16 v[124:125], v176 offset:0x1000+3072
	ds_read_b64_tr_b16 v[118:119], v176 offset:0x1000+64
	ds_read_b64_tr_b16 v[120:121], v176 offset:0x1000+64+1024
	ds_read_b64_tr_b16 v[114:115], v176 offset:0x1000+64+2048
	ds_read_b64_tr_b16 v[116:117], v176 offset:0x1000+64+3072
	ds_read_b64_tr_b16 v[50:51], v176 offset:0x2000
	ds_read_b64_tr_b16 v[52:53], v176 offset:0x2000+1024
	ds_read_b64_tr_b16 v[138:139], v176 offset:0x2000+2048
	ds_read_b64_tr_b16 v[140:141], v176 offset:0x2000+3072
	ds_read_b64_tr_b16 v[142:143], v176 offset:0x2000+64
	ds_read_b64_tr_b16 v[144:145], v176 offset:0x2000+64+1024
	ds_read_b64_tr_b16 v[130:131], v176 offset:0x2000+64+2048
	ds_read_b64_tr_b16 v[132:133], v176 offset:0x2000+64+3072
	s_waitcnt lgkmcnt(0)
	ds_read2_b64 v[242:245], v106 offset0:4 offset1:6
	v_mfma_f32_32x32x16_bf16 v[66:81], v[86:89], v[98:101], v[66:81]
	ds_read2_b64 v[98:101], v195 offset0:8 offset1:10
	v_cndmask_b32_e64 v44, v45, 0, s[82:83]
	v_cvt_pk_bf16_f32 v43, v43, v44
	v_cndmask_b32_e64 v44, v46, 0, s[84:85]
	v_mfma_f32_32x32x16_bf16 v[66:81], v[90:93], v[102:105], v[66:81]
	ds_read2_b64 v[102:105], v195 offset0:12 offset1:14
	v_mfma_f32_32x32x16_bf16 v[82:97], v[54:57], v[146:149], 0
	ds_read2_b64 v[54:57], v195 offset1:2
	s_nop 8
	v_cndmask_b32_e64 v0, v66, 0, s[62:63]
	v_cndmask_b32_e64 v62, 0, v67, s[0:1]
	v_cndmask_b32_e64 v63, v68, 0, s[64:65]
	v_cndmask_b32_e64 v64, v69, 0, s[66:67]
	v_cndmask_b32_e64 v65, v70, 0, s[68:69]
	v_cndmask_b32_e64 v66, v71, 0, s[70:71]
	v_mfma_f32_32x32x16_bf16 v[82:97], v[58:61], v[134:137], v[82:97]
	ds_read2_b64 v[58:61], v195 offset0:4 offset1:6
	v_cndmask_b32_e64 v67, v73, 0, s[74:75]
	v_cndmask_b32_e64 v213, v75, 0, s[78:79]
	v_cndmask_b32_e64 v218, v76, 0, s[80:81]
	v_cndmask_b32_e64 v219, v77, 0, s[82:83]
	v_cvt_pk_bf16_f32 v75, v12, v13
	v_cvt_pk_bf16_f32 v76, v14, v15
	s_waitcnt lgkmcnt(1)
	v_mfma_f32_32x32x16_bf16 v[82:97], v[54:57], v[214:217], v[82:97]
	v_cndmask_b32_e64 v57, v72, 0, s[72:73]
	v_cvt_pk_bf16_f32 v54, v0, v62
	v_cvt_pk_bf16_f32 v55, v63, v64
	v_cvt_pk_bf16_f32 v56, v65, v66
	v_cvt_pk_bf16_f32 v57, v57, v67
	v_cndmask_b32_e64 v0, v74, 0, s[76:77]
	v_cvt_pk_bf16_f32 v74, v10, v11
	s_waitcnt lgkmcnt(0)
	v_mfma_f32_32x32x16_bf16 v[82:97], v[58:61], v[228:231], v[82:97]
	v_cvt_pk_bf16_f32 v77, v16, v17
	v_cndmask_b32_e64 v237, v78, 0, s[84:85]
	v_cndmask_b32_e64 v246, v79, 0, s[86:87]
	v_cvt_pk_bf16_f32 v78, v0, v213
	v_cvt_pk_bf16_f32 v79, v218, v219
	v_add_u32_e32 v0, 0x3000, v195
	v_mfma_f32_32x32x16_bf16 v[58:73], v[54:57], v[146:149], 0
	v_cvt_pk_bf16_f32 v54, v2, v3
	v_cvt_pk_bf16_f32 v55, v4, v5
	v_cvt_pk_bf16_f32 v56, v6, v7
	v_cvt_pk_bf16_f32 v57, v8, v9
	s_nop 1
	v_mfma_f32_32x32x16_bf16 v[82:97], v[98:101], v[54:57], v[82:97]
	ds_read2_b64 v[98:101], v106 offset1:2
	v_mfma_f32_32x32x16_bf16 v[82:97], v[102:105], v[74:77], v[82:97]
	s_nop 11
	v_cvt_pk_bf16_f32 v82, v82, v83
	v_cvt_pk_bf16_f32 v83, v84, v85
	v_cvt_pk_bf16_f32 v84, v86, v87
	v_cvt_pk_bf16_f32 v85, v88, v89
	s_waitcnt lgkmcnt(0)
	s_nop 0
	v_mfma_f32_32x32x16_bf16 v[98:113], v[98:101], v[82:85], 0
	v_cndmask_b32_e64 v84, v80, 0, s[88:89]
	v_cndmask_b32_e64 v85, v81, 0, s[90:91]
	v_cvt_pk_bf16_f32 v80, v90, v91
	v_cvt_pk_bf16_f32 v81, v92, v93
	v_cvt_pk_bf16_f32 v82, v94, v95
	v_cvt_pk_bf16_f32 v83, v96, v97
	ds_read2_b64 v[90:93], v0 offset0:4 offset1:6
	s_nop 0
	v_mfma_f32_32x32x16_bf16 v[98:113], v[242:245], v[80:83], v[98:113]
	v_cvt_pk_bf16_f32 v80, v237, v246
	v_cvt_pk_bf16_f32 v81, v84, v85
	ds_read2_b64 v[82:85], v0 offset1:2
	s_nop 0
	v_mfma_f32_32x32x16_bf16 v[58:73], v[78:81], v[134:137], v[58:73]
	s_nop 6
	v_cvt_pk_bf16_f32 v86, v98, v99
	v_cvt_pk_bf16_f32 v87, v100, v101
	v_cvt_pk_bf16_f32 v88, v102, v103
	v_cvt_pk_bf16_f32 v89, v104, v105
	v_cvt_pk_bf16_f32 v78, v106, v107
	v_cvt_pk_bf16_f32 v79, v108, v109
	v_cvt_pk_bf16_f32 v80, v110, v111
	s_waitcnt lgkmcnt(0)
	v_mfma_f32_32x32x16_bf16 v[58:73], v[82:85], v[214:217], v[58:73]
	ds_read2_b64 v[82:85], v0 offset0:8 offset1:10
	v_cvt_pk_bf16_f32 v81, v112, v113
	v_mfma_f32_32x32x16_bf16 v[58:73], v[90:93], v[228:231], v[58:73]
	ds_read2_b64 v[90:93], v0 offset0:12 offset1:14
	v_cndmask_b32_e64 v0, v36, 0, s[64:65]
	v_cndmask_b32_e64 v36, v37, 0, s[66:67]
	v_cndmask_b32_e64 v37, v38, 0, s[68:69]
	v_cndmask_b32_e64 v38, v39, 0, s[70:71]
	v_cndmask_b32_e64 v39, v40, 0, s[72:73]
	v_cndmask_b32_e64 v40, v41, 0, s[74:75]
	s_waitcnt lgkmcnt(1)
	v_mfma_f32_32x32x16_bf16 v[58:73], v[82:85], v[54:57], v[58:73]
	v_cvt_pk_bf16_f32 v35, v0, v36
	v_cvt_pk_bf16_f32 v36, v37, v38
	v_cvt_pk_bf16_f32 v37, v39, v40
	v_cndmask_b32_e64 v0, v47, 0, s[86:87]
	v_cvt_pk_bf16_f32 v44, v44, v0
	v_cndmask_b32_e64 v0, v48, 0, s[88:89]
	v_cndmask_b32_e64 v38, v49, 0, s[90:91]
	s_waitcnt lgkmcnt(0)
	v_mfma_f32_32x32x16_bf16 v[58:73], v[90:93], v[74:77], v[58:73]
	v_cvt_pk_bf16_f32 v45, v0, v38
	v_mfma_f32_32x32x16_bf16 v[58:73], v[34:37], v[86:89], v[58:73]
	v_add_u32_e32 v34, s8, v155
	v_ashrrev_i32_e32 v35, 31, v34
	v_lshlrev_b64 v[34:35], 12, v[34:35]
	v_lshl_add_u64 v[34:35], v[158:159], 0, v[34:35]
	v_mfma_f32_32x32x16_bf16 v[58:73], v[42:45], v[78:81], v[58:73]
	v_mfma_f32_32x32x16_bf16 v[18:33], v[126:129], v[86:89], v[18:33]
	s_nop 10
	global_store_dword v[34:35], v58, off
	v_add_u32_e32 v34, s8, v197
	v_ashrrev_i32_e32 v35, 31, v34
	v_lshlrev_b64 v[34:35], 12, v[34:35]
	v_lshl_add_u64 v[34:35], v[158:159], 0, v[34:35]
	global_store_dword v[34:35], v59, off
	v_add_u32_e32 v34, s8, v198
	v_ashrrev_i32_e32 v35, 31, v34
	v_lshlrev_b64 v[34:35], 12, v[34:35]
	v_lshl_add_u64 v[34:35], v[158:159], 0, v[34:35]
	global_store_dword v[34:35], v60, off
	v_add_u32_e32 v34, s8, v199
	v_ashrrev_i32_e32 v35, 31, v34
	v_lshlrev_b64 v[34:35], 12, v[34:35]
	v_lshl_add_u64 v[34:35], v[158:159], 0, v[34:35]
	global_store_dword v[34:35], v61, off
	v_add_u32_e32 v34, s8, v200
	v_ashrrev_i32_e32 v35, 31, v34
	v_lshlrev_b64 v[34:35], 12, v[34:35]
	v_lshl_add_u64 v[34:35], v[158:159], 0, v[34:35]
	global_store_dword v[34:35], v62, off
	v_add_u32_e32 v34, s8, v201
	v_ashrrev_i32_e32 v35, 31, v34
	v_lshlrev_b64 v[34:35], 12, v[34:35]
	v_lshl_add_u64 v[34:35], v[158:159], 0, v[34:35]
	global_store_dword v[34:35], v63, off
	v_add_u32_e32 v34, s8, v202
	v_ashrrev_i32_e32 v35, 31, v34
	v_lshlrev_b64 v[34:35], 12, v[34:35]
	v_lshl_add_u64 v[34:35], v[158:159], 0, v[34:35]
	global_store_dword v[34:35], v64, off
	v_add_u32_e32 v34, s8, v203
	v_ashrrev_i32_e32 v35, 31, v34
	v_lshlrev_b64 v[34:35], 12, v[34:35]
	v_lshl_add_u64 v[34:35], v[158:159], 0, v[34:35]
	global_store_dword v[34:35], v65, off
	v_add_u32_e32 v34, s8, v204
	v_ashrrev_i32_e32 v35, 31, v34
	v_lshlrev_b64 v[34:35], 12, v[34:35]
	v_lshl_add_u64 v[34:35], v[158:159], 0, v[34:35]
	global_store_dword v[34:35], v66, off
	v_add_u32_e32 v34, s8, v205
	v_ashrrev_i32_e32 v35, 31, v34
	v_lshlrev_b64 v[34:35], 12, v[34:35]
	v_lshl_add_u64 v[34:35], v[158:159], 0, v[34:35]
	v_add_u32_e32 v66, s8, v206
	global_store_dword v[34:35], v67, off
	v_ashrrev_i32_e32 v67, 31, v66
	v_lshlrev_b64 v[66:67], 12, v[66:67]
	v_lshl_add_u64 v[66:67], v[158:159], 0, v[66:67]
	global_store_dword v[66:67], v68, off
	v_add_u32_e32 v66, s8, v207
	v_ashrrev_i32_e32 v67, 31, v66
	v_lshlrev_b64 v[66:67], 12, v[66:67]
	v_lshl_add_u64 v[66:67], v[158:159], 0, v[66:67]
	global_store_dword v[66:67], v69, off
	v_add_u32_e32 v66, s8, v208
	v_ashrrev_i32_e32 v67, 31, v66
	v_lshlrev_b64 v[66:67], 12, v[66:67]
	v_lshl_add_u64 v[66:67], v[158:159], 0, v[66:67]
	global_store_dword v[66:67], v70, off
	v_add_u32_e32 v66, s8, v209
	v_ashrrev_i32_e32 v67, 31, v66
	v_lshlrev_b64 v[66:67], 12, v[66:67]
	v_lshl_add_u64 v[66:67], v[158:159], 0, v[66:67]
	global_store_dword v[66:67], v71, off
	v_add_u32_e32 v66, s8, v210
	v_mfma_f32_32x32x16_bf16 v[34:49], v[142:145], v[146:149], 0
	v_ashrrev_i32_e32 v67, 31, v66
	v_lshlrev_b64 v[66:67], 12, v[66:67]
	v_lshl_add_u64 v[66:67], v[158:159], 0, v[66:67]
	global_store_dword v[66:67], v72, off
	v_add_u32_e32 v66, s8, v211
	v_ashrrev_i32_e32 v67, 31, v66
	v_lshlrev_b64 v[66:67], 12, v[66:67]
	v_mfma_f32_32x32x16_bf16 v[50:65], v[50:53], v[146:149], 0
	v_lshl_add_u64 v[66:67], v[158:159], 0, v[66:67]
	global_store_dword v[66:67], v73, off
	v_add_u32_e32 v144, s22, v160
	s_cselect_b64 s[8:9], -1, 0
	s_and_b64 vcc, exec, s[8:9]
	v_mfma_f32_32x32x16_bf16 v[2:17], v[118:121], v[86:89], v[2:17]
	v_mfma_f32_32x32x16_bf16 v[34:49], v[130:133], v[134:137], v[34:49]
	v_mfma_f32_32x32x16_bf16 v[18:33], v[122:125], v[78:81], v[18:33]
	ds_read_b128 v[130:133], v144 offset:22528
	ds_read_b128 v[126:129], v144 offset:22560
	ds_read_b128 v[122:125], v144 offset:22592
	ds_read_b128 v[108:111], v144 offset:22624
	ds_read_b128 v[100:103], v144 offset:22656
	ds_read_b128 v[96:99], v144 offset:22688
	ds_read_b128 v[104:107], v144 offset:22720
	ds_read_b128 v[92:95], v144 offset:22752
	s_waitcnt vmcnt(16)
	v_mfma_f32_32x32x16_bf16 v[50:65], v[138:141], v[134:137], v[50:65]
	v_mfma_f32_32x32x16_bf16 v[2:17], v[114:117], v[78:81], v[2:17]
	s_cbranch_vccnz .LBB0_983
	s_and_b64 s[14:15], s[92:93], exec
	v_mov_b32_e32 v67, v234
	s_cselect_b32 s14, s18, s20
	s_add_i32 s14, s14, s13
	v_ashrrev_i32_e32 v0, 3, v67
	v_sub_u32_e32 v68, 31, v0
	s_lshl_b32 s15, s14, 5
	v_cndmask_b32_e64 v0, v68, v0, s[92:93]
	v_add_u32_e32 v68, s15, v0
	v_ashrrev_i32_e32 v69, 31, v68
	v_lshlrev_b64 v[68:69], 4, v[68:69]
	v_or_b32_e32 v0, s26, v68
	v_mov_b64_e32 v[70:71], s[94:95]
	v_mad_u64_u32 v[72:73], vcc, v0, s33, v[70:71]
	v_lshlrev_b32_e32 v74, 4, v67
	v_mad_i32_i24 v73, v69, s33, v73
	v_and_b32_e32 v0, 0x70, v74
	v_lshl_add_u64 v[68:69], v[72:73], 0, v[0:1]
	s_mov_b32 m0, s22
	s_nop 0
	global_load_lds_dwordx4 v[68:69], off
	s_mov_b64 s[6:7], 0x80
	v_lshl_add_u64 v[72:73], v[68:69], 0, s[6:7]
	s_mov_b32 m0, s19
	s_nop 0
	global_load_lds_dwordx4 v[72:73], off
	s_mov_b64 s[4:5], 0x100
	v_readlane_b32 s24, v255, 4
	v_lshl_add_u64 v[72:73], v[68:69], 0, s[4:5]
	s_mov_b32 m0, s24
	s_nop 0
	global_load_lds_dwordx4 v[72:73], off
	s_mov_b64 s[30:31], 0x180
	v_readlane_b32 s24, v255, 5
	s_lshl_b64 vcc, s[96:97], 1
	v_lshl_add_u64 v[72:73], v[68:69], 0, s[30:31]
	s_mov_b32 m0, s24
	s_nop 0
	global_load_lds_dwordx4 v[72:73], off
	v_lshl_add_u64 v[68:69], v[68:69], 0, vcc
	s_mov_b64 s[24:25], 0x400
	v_lshl_add_u64 v[68:69], v[68:69], 0, s[24:25]
	v_readlane_b32 s29, v255, 9
	s_mov_b32 m0, s29
	s_nop 0
	global_load_lds_dwordx4 v[68:69], off
	v_add_u32_e32 v68, 64, v67
	v_ashrrev_i32_e32 v68, 3, v68
	v_sub_u32_e32 v69, 31, v68
	v_cndmask_b32_e64 v68, v69, v68, s[92:93]
	v_add_u32_e32 v68, s15, v68
	v_ashrrev_i32_e32 v69, 31, v68
	v_lshlrev_b64 v[68:69], 4, v[68:69]
	v_or_b32_e32 v68, s26, v68
	v_mad_u64_u32 v[72:73], s[28:29], v68, s33, v[70:71]
	v_mad_i32_i24 v73, v69, s33, v73
	v_lshl_add_u64 v[68:69], v[72:73], 0, v[0:1]
	v_readlane_b32 s29, v255, 2
	s_mov_b32 m0, s29
	s_nop 0
	global_load_lds_dwordx4 v[68:69], off
	v_lshl_add_u64 v[72:73], v[68:69], 0, s[6:7]
	v_readlane_b32 s29, v255, 3
	s_mov_b32 m0, s29
	s_nop 0
	global_load_lds_dwordx4 v[72:73], off
	v_lshl_add_u64 v[72:73], v[68:69], 0, s[4:5]
	v_readlane_b32 s29, v255, 41
	s_mov_b32 m0, s29
	s_nop 0
	global_load_lds_dwordx4 v[72:73], off
	v_lshl_add_u64 v[72:73], v[68:69], 0, s[30:31]
	v_lshl_add_u64 v[68:69], v[68:69], 0, vcc
	v_readlane_b32 s29, v255, 42
	s_mov_b32 m0, s29
	s_nop 0
	global_load_lds_dwordx4 v[72:73], off
	v_lshl_add_u64 v[68:69], v[68:69], 0, s[24:25]
	v_readlane_b32 s29, v255, 43
	s_mov_b32 m0, s29
	s_nop 0
	global_load_lds_dwordx4 v[68:69], off
	v_add_u32_e32 v68, 0x80, v67
	v_ashrrev_i32_e32 v68, 3, v68
	v_sub_u32_e32 v69, 31, v68
	v_cndmask_b32_e64 v68, v69, v68, s[92:93]
	v_add_u32_e32 v68, s15, v68
	v_ashrrev_i32_e32 v69, 31, v68
	v_lshlrev_b64 v[68:69], 4, v[68:69]
	v_or_b32_e32 v68, s26, v68
	v_mad_u64_u32 v[72:73], s[28:29], v68, s33, v[70:71]
	v_mad_i32_i24 v73, v69, s33, v73
	v_lshl_add_u64 v[68:69], v[72:73], 0, v[0:1]
	v_readlane_b32 s29, v255, 44
	s_mov_b32 m0, s29
	s_nop 0
	global_load_lds_dwordx4 v[68:69], off
	v_lshl_add_u64 v[72:73], v[68:69], 0, s[6:7]
	v_readlane_b32 s29, v255, 45
	s_mov_b32 m0, s29
	s_nop 0
	global_load_lds_dwordx4 v[72:73], off
	v_lshl_add_u64 v[72:73], v[68:69], 0, s[4:5]
	v_lshlrev_b32_e32 v66, 3, v67
	v_readlane_b32 s29, v255, 46
	s_mov_b32 m0, s29
	s_nop 0
	global_load_lds_dwordx4 v[72:73], off
	v_lshl_add_u64 v[72:73], v[68:69], 0, s[30:31]
	v_lshl_add_u64 v[68:69], v[68:69], 0, vcc
	v_add_u32_e32 v67, 0xc0, v67
	v_readlane_b32 s29, v255, 47
	s_mov_b32 m0, s29
	s_nop 0
	global_load_lds_dwordx4 v[72:73], off
	v_lshl_add_u64 v[68:69], v[68:69], 0, s[24:25]
	v_ashrrev_i32_e32 v67, 3, v67
	v_readlane_b32 s29, v255, 48
	s_mov_b32 m0, s29
	s_nop 0
	global_load_lds_dwordx4 v[68:69], off
	v_sub_u32_e32 v68, 31, v67
	v_cndmask_b32_e64 v67, v68, v67, s[92:93]
	v_add_u32_e32 v68, s15, v67
	v_ashrrev_i32_e32 v69, 31, v68
	v_lshlrev_b64 v[68:69], 4, v[68:69]
	v_or_b32_e32 v67, s26, v68
	v_mad_u64_u32 v[70:71], s[28:29], v67, s33, v[70:71]
	v_mad_i32_i24 v71, v69, s33, v71
	v_lshl_add_u64 v[68:69], v[70:71], 0, v[0:1]
	v_readlane_b32 s28, v255, 49
	s_mov_b32 m0, s28
	s_nop 0
	global_load_lds_dwordx4 v[68:69], off
	v_lshl_add_u64 v[70:71], v[68:69], 0, s[6:7]
	v_readlane_b32 s6, v255, 50
	s_mov_b32 m0, s6
	s_nop 0
	global_load_lds_dwordx4 v[70:71], off
	v_lshl_add_u64 v[70:71], v[68:69], 0, s[4:5]
	v_readlane_b32 s4, v255, 51
	s_mov_b32 m0, s4
	s_nop 0
	global_load_lds_dwordx4 v[70:71], off
	v_lshl_add_u64 v[70:71], v[68:69], 0, s[30:31]
	v_readlane_b32 s4, v255, 52
	s_mov_b32 m0, s4
	s_nop 0
	global_load_lds_dwordx4 v[70:71], off
	v_lshl_add_u64 v[68:69], v[68:69], 0, vcc
	v_lshl_add_u64 v[68:69], v[68:69], 0, s[24:25]
	v_readlane_b32 s4, v255, 53
	s_mov_b32 m0, s4
	s_nop 0
	global_load_lds_dwordx4 v[68:69], off
	s_ashr_i32 s15, s14, 31
	s_lshl_b64 s[14:15], s[14:15], 5
	s_or_b64 s[14:15], s[14:15], s[16:17]
	s_lshl_b64 s[28:29], s[14:15], 11
	v_readlane_b32 s4, v255, 6
	s_add_u32 s28, s4, s28
	v_readlane_b32 s4, v255, 0
	s_addc_u32 s29, s4, s29
	v_ashrrev_i32_e32 v67, 31, v66
	s_lshl_b64 s[14:15], s[14:15], 8
	v_lshl_add_u64 v[66:67], v[66:67], 1, s[28:29]
	v_readlane_b32 s4, v255, 10
	s_mov_b32 m0, s4
	s_nop 0
	global_load_lds_dwordx4 v[66:67], off
	s_add_u32 s14, s27, s14
	v_lshl_add_u64 v[66:67], v[66:67], 0, s[24:25]
	v_readlane_b32 s4, v255, 54
	s_mov_b32 m0, s4
	s_nop 0
	global_load_lds_dwordx4 v[66:67], off
	s_addc_u32 s15, s23, s15
	v_and_b32_e32 v0, 0xf0, v74
	v_lshl_add_u64 v[66:67], s[14:15], 0, v[0:1]
	v_readlane_b32 s4, v255, 11
	s_mov_b32 m0, s4
	s_nop 0
	global_load_lds_dwordx4 v[66:67], off
	s_movk_i32 s29, 0x7c00
	s_branch .LBB0_983
